# adds: EpiSwiglu body hand-written with packed f32 mul/fma, software-pipelined over 32 output pairs, 24-bit row address multiply
# speedup vs baseline: 1.0010x; 1.0010x over previous
.LBB0_78:
	s_waitcnt lgkmcnt(0)
	v_lshl_or_b32 v192, s2, 7, v173
	v_lshlrev_b32_e32 v192, 1, v192
	v_mul_f32_e32 v182, v170, v170
	v_mul_f32_e32 v180, 0xbfb8aa3b, v170
	v_rcp_f32_e32 v182, v182
	v_pk_mul_f32 v[122:123], v[126:127], v[122:123]
	v_pk_mul_f32 v[124:125], v[128:129], v[124:125]
	v_pk_mul_f32 v[126:127], v[126:127], v[180:181] op_sel_hi:[1,0]
	v_pk_mul_f32 v[114:115], v[118:119], v[114:115]
	v_pk_mul_f32 v[128:129], v[128:129], v[180:181] op_sel_hi:[1,0]
	v_exp_f32_e32 v126, v126
	v_exp_f32_e32 v127, v127
	v_mul_f32_e32 v186, v171, v171
	v_mul_f32_e32 v184, 0xbfb8aa3b, v171
	v_rcp_f32_e32 v186, v186
	v_pk_mul_f32 v[116:117], v[120:121], v[116:117]
	v_pk_mul_f32 v[118:119], v[118:119], v[180:181] op_sel_hi:[1,0]
	v_exp_f32_e32 v128, v128
	v_exp_f32_e32 v129, v129
	v_pk_fma_f32 v[126:127], v[126:127], v[182:183], v[182:183] op_sel_hi:[1,0,0]
	v_pk_mul_f32 v[106:107], v[110:111], v[106:107]
	v_pk_mul_f32 v[120:121], v[120:121], v[180:181] op_sel_hi:[1,0]
	v_exp_f32_e32 v118, v118
	v_exp_f32_e32 v119, v119
	v_pk_fma_f32 v[128:129], v[128:129], v[182:183], v[182:183] op_sel_hi:[1,0,0]
	v_rcp_f32_e32 v126, v126
	v_rcp_f32_e32 v127, v127
	v_pk_mul_f32 v[108:109], v[112:113], v[108:109]
	v_pk_mul_f32 v[110:111], v[110:111], v[184:185] op_sel_hi:[1,0]
	v_exp_f32_e32 v120, v120
	v_exp_f32_e32 v121, v121
	v_pk_fma_f32 v[118:119], v[118:119], v[182:183], v[182:183] op_sel_hi:[1,0,0]
	v_rcp_f32_e32 v128, v128
	v_rcp_f32_e32 v129, v129
	v_pk_mul_f32 v[122:123], v[122:123], v[126:127]
	v_pk_mul_f32 v[98:99], v[102:103], v[98:99]
	v_pk_mul_f32 v[112:113], v[112:113], v[184:185] op_sel_hi:[1,0]
	v_exp_f32_e32 v110, v110
	v_exp_f32_e32 v111, v111
	v_pk_fma_f32 v[120:121], v[120:121], v[182:183], v[182:183] op_sel_hi:[1,0,0]
	v_rcp_f32_e32 v118, v118
	v_rcp_f32_e32 v119, v119
	v_pk_mul_f32 v[124:125], v[124:125], v[128:129]
	v_mul_f32_e32 v182, v162, v162
	v_mul_f32_e32 v180, 0xbfb8aa3b, v162
	v_rcp_f32_e32 v182, v182
	v_pk_mul_f32 v[100:101], v[104:105], v[100:101]
	v_pk_mul_f32 v[102:103], v[102:103], v[184:185] op_sel_hi:[1,0]
	v_exp_f32_e32 v112, v112
	v_exp_f32_e32 v113, v113
	v_pk_fma_f32 v[110:111], v[110:111], v[186:187], v[186:187] op_sel_hi:[1,0,0]
	v_rcp_f32_e32 v120, v120
	v_rcp_f32_e32 v121, v121
	v_pk_mul_f32 v[114:115], v[114:115], v[118:119]
	v_pk_mul_f32 v[88:89], v[92:93], v[88:89]
	v_pk_mul_f32 v[104:105], v[104:105], v[184:185] op_sel_hi:[1,0]
	v_exp_f32_e32 v102, v102
	v_exp_f32_e32 v103, v103
	v_pk_fma_f32 v[112:113], v[112:113], v[186:187], v[186:187] op_sel_hi:[1,0,0]
	v_rcp_f32_e32 v110, v110
	v_rcp_f32_e32 v111, v111
	v_pk_mul_f32 v[116:117], v[116:117], v[120:121]
	v_pk_mul_f32 v[90:91], v[94:95], v[90:91]
	v_pk_mul_f32 v[92:93], v[92:93], v[180:181] op_sel_hi:[1,0]
	v_exp_f32_e32 v104, v104
	v_exp_f32_e32 v105, v105
	v_pk_fma_f32 v[102:103], v[102:103], v[186:187], v[186:187] op_sel_hi:[1,0,0]
	v_rcp_f32_e32 v112, v112
	v_rcp_f32_e32 v113, v113
	v_pk_mul_f32 v[106:107], v[106:107], v[110:111]
	v_mul_u32_u24_e32 v188, s65, v168
	v_mov_b32_e32 v189, 0
	v_cvt_pk_bf16_f32 v126, v122, v123
	v_cvt_pk_bf16_f32 v127, v124, v125
	v_cvt_pk_bf16_f32 v128, v114, v115
	v_cvt_pk_bf16_f32 v129, v116, v117
	v_add_u32_e32 v188, v188, v192
	v_lshl_add_u64 v[188:189], v[188:189], 0, s[8:9]
	s_nop 0
	global_store_dwordx4 v[188:189], v[126:129], off
	v_pk_mul_f32 v[80:81], v[84:85], v[80:81]
	v_pk_mul_f32 v[94:95], v[94:95], v[180:181] op_sel_hi:[1,0]
	v_exp_f32_e32 v92, v92
	v_exp_f32_e32 v93, v93
	v_pk_fma_f32 v[104:105], v[104:105], v[186:187], v[186:187] op_sel_hi:[1,0,0]
	v_rcp_f32_e32 v102, v102
	v_rcp_f32_e32 v103, v103
	v_pk_mul_f32 v[108:109], v[108:109], v[112:113]
	v_mul_f32_e32 v186, v163, v163
	v_mul_f32_e32 v184, 0xbfb8aa3b, v163
	v_rcp_f32_e32 v186, v186
	v_pk_mul_f32 v[82:83], v[86:87], v[82:83]
	v_pk_mul_f32 v[84:85], v[84:85], v[180:181] op_sel_hi:[1,0]
	v_exp_f32_e32 v94, v94
	v_exp_f32_e32 v95, v95
	v_pk_fma_f32 v[92:93], v[92:93], v[182:183], v[182:183] op_sel_hi:[1,0,0]
	v_rcp_f32_e32 v104, v104
	v_rcp_f32_e32 v105, v105
	v_pk_mul_f32 v[98:99], v[98:99], v[102:103]
	v_pk_mul_f32 v[72:73], v[76:77], v[72:73]
	v_pk_mul_f32 v[86:87], v[86:87], v[180:181] op_sel_hi:[1,0]
	v_exp_f32_e32 v84, v84
	v_exp_f32_e32 v85, v85
	v_pk_fma_f32 v[94:95], v[94:95], v[182:183], v[182:183] op_sel_hi:[1,0,0]
	v_rcp_f32_e32 v92, v92
	v_rcp_f32_e32 v93, v93
	v_pk_mul_f32 v[100:101], v[100:101], v[104:105]
	v_pk_mul_f32 v[74:75], v[78:79], v[74:75]
	v_pk_mul_f32 v[76:77], v[76:77], v[184:185] op_sel_hi:[1,0]
	v_exp_f32_e32 v86, v86
	v_exp_f32_e32 v87, v87
	v_pk_fma_f32 v[84:85], v[84:85], v[182:183], v[182:183] op_sel_hi:[1,0,0]
	v_rcp_f32_e32 v94, v94
	v_rcp_f32_e32 v95, v95
	v_pk_mul_f32 v[88:89], v[88:89], v[92:93]
	v_mul_u32_u24_e32 v190, s65, v164
	v_mov_b32_e32 v191, 0
	v_cvt_pk_bf16_f32 v110, v106, v107
	v_cvt_pk_bf16_f32 v111, v108, v109
	v_cvt_pk_bf16_f32 v112, v98, v99
	v_cvt_pk_bf16_f32 v113, v100, v101
	v_add_u32_e32 v190, v190, v192
	v_lshl_add_u64 v[190:191], v[190:191], 0, s[8:9]
	s_nop 0
	global_store_dwordx4 v[190:191], v[110:113], off
	v_pk_mul_f32 v[64:65], v[68:69], v[64:65]
	v_pk_mul_f32 v[78:79], v[78:79], v[184:185] op_sel_hi:[1,0]
	v_exp_f32_e32 v76, v76
	v_exp_f32_e32 v77, v77
	v_pk_fma_f32 v[86:87], v[86:87], v[182:183], v[182:183] op_sel_hi:[1,0,0]
	v_rcp_f32_e32 v84, v84
	v_rcp_f32_e32 v85, v85
	v_pk_mul_f32 v[90:91], v[90:91], v[94:95]
	v_mul_f32_e32 v182, v158, v158
	v_mul_f32_e32 v180, 0xbfb8aa3b, v158
	v_rcp_f32_e32 v182, v182
	v_pk_mul_f32 v[66:67], v[70:71], v[66:67]
	v_pk_mul_f32 v[68:69], v[68:69], v[184:185] op_sel_hi:[1,0]
	v_exp_f32_e32 v78, v78
	v_exp_f32_e32 v79, v79
	v_pk_fma_f32 v[76:77], v[76:77], v[186:187], v[186:187] op_sel_hi:[1,0,0]
	v_rcp_f32_e32 v86, v86
	v_rcp_f32_e32 v87, v87
	v_pk_mul_f32 v[80:81], v[80:81], v[84:85]
	v_pk_mul_f32 v[56:57], v[60:61], v[56:57]
	v_pk_mul_f32 v[70:71], v[70:71], v[184:185] op_sel_hi:[1,0]
	v_exp_f32_e32 v68, v68
	v_exp_f32_e32 v69, v69
	v_pk_fma_f32 v[78:79], v[78:79], v[186:187], v[186:187] op_sel_hi:[1,0,0]
	v_rcp_f32_e32 v76, v76
	v_rcp_f32_e32 v77, v77
	v_pk_mul_f32 v[82:83], v[82:83], v[86:87]
	v_pk_mul_f32 v[58:59], v[62:63], v[58:59]
	v_pk_mul_f32 v[60:61], v[60:61], v[180:181] op_sel_hi:[1,0]
	v_exp_f32_e32 v70, v70
	v_exp_f32_e32 v71, v71
	v_pk_fma_f32 v[68:69], v[68:69], v[186:187], v[186:187] op_sel_hi:[1,0,0]
	v_rcp_f32_e32 v78, v78
	v_rcp_f32_e32 v79, v79
	v_pk_mul_f32 v[72:73], v[72:73], v[76:77]
	v_mul_u32_u24_e32 v188, s65, v160
	v_mov_b32_e32 v189, 0
	v_cvt_pk_bf16_f32 v92, v88, v89
	v_cvt_pk_bf16_f32 v93, v90, v91
	v_cvt_pk_bf16_f32 v94, v80, v81
	v_cvt_pk_bf16_f32 v95, v82, v83
	v_add_u32_e32 v188, v188, v192
	v_lshl_add_u64 v[188:189], v[188:189], 0, s[8:9]
	s_nop 0
	global_store_dwordx4 v[188:189], v[92:95], off
	v_pk_mul_f32 v[48:49], v[52:53], v[48:49]
	v_pk_mul_f32 v[62:63], v[62:63], v[180:181] op_sel_hi:[1,0]
	v_exp_f32_e32 v60, v60
	v_exp_f32_e32 v61, v61
	v_pk_fma_f32 v[70:71], v[70:71], v[186:187], v[186:187] op_sel_hi:[1,0,0]
	v_rcp_f32_e32 v68, v68
	v_rcp_f32_e32 v69, v69
	v_pk_mul_f32 v[74:75], v[74:75], v[78:79]
	v_mul_f32_e32 v186, v159, v159
	v_mul_f32_e32 v184, 0xbfb8aa3b, v159
	v_rcp_f32_e32 v186, v186
	v_pk_mul_f32 v[50:51], v[54:55], v[50:51]
	v_pk_mul_f32 v[52:53], v[52:53], v[180:181] op_sel_hi:[1,0]
	v_exp_f32_e32 v62, v62
	v_exp_f32_e32 v63, v63
	v_pk_fma_f32 v[60:61], v[60:61], v[182:183], v[182:183] op_sel_hi:[1,0,0]
	v_rcp_f32_e32 v70, v70
	v_rcp_f32_e32 v71, v71
	v_pk_mul_f32 v[64:65], v[64:65], v[68:69]
	v_pk_mul_f32 v[40:41], v[44:45], v[40:41]
	v_pk_mul_f32 v[54:55], v[54:55], v[180:181] op_sel_hi:[1,0]
	v_exp_f32_e32 v52, v52
	v_exp_f32_e32 v53, v53
	v_pk_fma_f32 v[62:63], v[62:63], v[182:183], v[182:183] op_sel_hi:[1,0,0]
	v_rcp_f32_e32 v60, v60
	v_rcp_f32_e32 v61, v61
	v_pk_mul_f32 v[66:67], v[66:67], v[70:71]
	v_pk_mul_f32 v[42:43], v[46:47], v[42:43]
	v_pk_mul_f32 v[44:45], v[44:45], v[184:185] op_sel_hi:[1,0]
	v_exp_f32_e32 v54, v54
	v_exp_f32_e32 v55, v55
	v_pk_fma_f32 v[52:53], v[52:53], v[182:183], v[182:183] op_sel_hi:[1,0,0]
	v_rcp_f32_e32 v62, v62
	v_rcp_f32_e32 v63, v63
	v_pk_mul_f32 v[56:57], v[56:57], v[60:61]
	v_mul_u32_u24_e32 v190, s65, v156
	v_mov_b32_e32 v191, 0
	v_cvt_pk_bf16_f32 v76, v72, v73
	v_cvt_pk_bf16_f32 v77, v74, v75
	v_cvt_pk_bf16_f32 v78, v64, v65
	v_cvt_pk_bf16_f32 v79, v66, v67
	v_add_u32_e32 v190, v190, v192
	v_lshl_add_u64 v[190:191], v[190:191], 0, s[8:9]
	s_nop 0
	global_store_dwordx4 v[190:191], v[76:79], off
	v_pk_mul_f32 v[32:33], v[36:37], v[32:33]
	v_pk_mul_f32 v[46:47], v[46:47], v[184:185] op_sel_hi:[1,0]
	v_exp_f32_e32 v44, v44
	v_exp_f32_e32 v45, v45
	v_pk_fma_f32 v[54:55], v[54:55], v[182:183], v[182:183] op_sel_hi:[1,0,0]
	v_rcp_f32_e32 v52, v52
	v_rcp_f32_e32 v53, v53
	v_pk_mul_f32 v[58:59], v[58:59], v[62:63]
	v_mul_f32_e32 v182, v152, v152
	v_mul_f32_e32 v180, 0xbfb8aa3b, v152
	v_rcp_f32_e32 v182, v182
	v_pk_mul_f32 v[34:35], v[38:39], v[34:35]
	v_pk_mul_f32 v[36:37], v[36:37], v[184:185] op_sel_hi:[1,0]
	v_exp_f32_e32 v46, v46
	v_exp_f32_e32 v47, v47
	v_pk_fma_f32 v[44:45], v[44:45], v[186:187], v[186:187] op_sel_hi:[1,0,0]
	v_rcp_f32_e32 v54, v54
	v_rcp_f32_e32 v55, v55
	v_pk_mul_f32 v[48:49], v[48:49], v[52:53]
	v_pk_mul_f32 v[24:25], v[28:29], v[24:25]
	v_pk_mul_f32 v[38:39], v[38:39], v[184:185] op_sel_hi:[1,0]
	v_exp_f32_e32 v36, v36
	v_exp_f32_e32 v37, v37
	v_pk_fma_f32 v[46:47], v[46:47], v[186:187], v[186:187] op_sel_hi:[1,0,0]
	v_rcp_f32_e32 v44, v44
	v_rcp_f32_e32 v45, v45
	v_pk_mul_f32 v[50:51], v[50:51], v[54:55]
	v_pk_mul_f32 v[26:27], v[30:31], v[26:27]
	v_pk_mul_f32 v[28:29], v[28:29], v[180:181] op_sel_hi:[1,0]
	v_exp_f32_e32 v38, v38
	v_exp_f32_e32 v39, v39
	v_pk_fma_f32 v[36:37], v[36:37], v[186:187], v[186:187] op_sel_hi:[1,0,0]
	v_rcp_f32_e32 v46, v46
	v_rcp_f32_e32 v47, v47
	v_pk_mul_f32 v[40:41], v[40:41], v[44:45]
	v_mul_u32_u24_e32 v188, s65, v154
	v_mov_b32_e32 v189, 0
	v_cvt_pk_bf16_f32 v60, v56, v57
	v_cvt_pk_bf16_f32 v61, v58, v59
	v_cvt_pk_bf16_f32 v62, v48, v49
	v_cvt_pk_bf16_f32 v63, v50, v51
	v_add_u32_e32 v188, v188, v192
	v_lshl_add_u64 v[188:189], v[188:189], 0, s[8:9]
	s_nop 0
	global_store_dwordx4 v[188:189], v[60:63], off
	v_pk_mul_f32 v[16:17], v[20:21], v[16:17]
	v_pk_mul_f32 v[30:31], v[30:31], v[180:181] op_sel_hi:[1,0]
	v_exp_f32_e32 v28, v28
	v_exp_f32_e32 v29, v29
	v_pk_fma_f32 v[38:39], v[38:39], v[186:187], v[186:187] op_sel_hi:[1,0,0]
	v_rcp_f32_e32 v36, v36
	v_rcp_f32_e32 v37, v37
	v_pk_mul_f32 v[42:43], v[42:43], v[46:47]
	v_mul_f32_e32 v186, v153, v153
	v_mul_f32_e32 v184, 0xbfb8aa3b, v153
	v_rcp_f32_e32 v186, v186
	v_pk_mul_f32 v[18:19], v[22:23], v[18:19]
	v_pk_mul_f32 v[20:21], v[20:21], v[180:181] op_sel_hi:[1,0]
	v_exp_f32_e32 v30, v30
	v_exp_f32_e32 v31, v31
	v_pk_fma_f32 v[28:29], v[28:29], v[182:183], v[182:183] op_sel_hi:[1,0,0]
	v_rcp_f32_e32 v38, v38
	v_rcp_f32_e32 v39, v39
	v_pk_mul_f32 v[32:33], v[32:33], v[36:37]
	v_pk_mul_f32 v[8:9], v[12:13], v[8:9]
	v_pk_mul_f32 v[22:23], v[22:23], v[180:181] op_sel_hi:[1,0]
	v_exp_f32_e32 v20, v20
	v_exp_f32_e32 v21, v21
	v_pk_fma_f32 v[30:31], v[30:31], v[182:183], v[182:183] op_sel_hi:[1,0,0]
	v_rcp_f32_e32 v28, v28
	v_rcp_f32_e32 v29, v29
	v_pk_mul_f32 v[34:35], v[34:35], v[38:39]
	v_pk_mul_f32 v[10:11], v[14:15], v[10:11]
	v_pk_mul_f32 v[12:13], v[12:13], v[184:185] op_sel_hi:[1,0]
	v_exp_f32_e32 v22, v22
	v_exp_f32_e32 v23, v23
	v_pk_fma_f32 v[20:21], v[20:21], v[182:183], v[182:183] op_sel_hi:[1,0,0]
	v_rcp_f32_e32 v30, v30
	v_rcp_f32_e32 v31, v31
	v_pk_mul_f32 v[24:25], v[24:25], v[28:29]
	v_mul_u32_u24_e32 v190, s65, v150
	v_mov_b32_e32 v191, 0
	v_cvt_pk_bf16_f32 v44, v40, v41
	v_cvt_pk_bf16_f32 v45, v42, v43
	v_cvt_pk_bf16_f32 v46, v32, v33
	v_cvt_pk_bf16_f32 v47, v34, v35
	v_add_u32_e32 v190, v190, v192
	v_lshl_add_u64 v[190:191], v[190:191], 0, s[8:9]
	s_nop 0
	global_store_dwordx4 v[190:191], v[44:47], off
	v_pk_mul_f32 v[0:1], v[4:5], v[0:1]
	v_pk_mul_f32 v[14:15], v[14:15], v[184:185] op_sel_hi:[1,0]
	v_exp_f32_e32 v12, v12
	v_exp_f32_e32 v13, v13
	v_pk_fma_f32 v[22:23], v[22:23], v[182:183], v[182:183] op_sel_hi:[1,0,0]
	v_rcp_f32_e32 v20, v20
	v_rcp_f32_e32 v21, v21
	v_pk_mul_f32 v[26:27], v[26:27], v[30:31]
	v_pk_mul_f32 v[2:3], v[6:7], v[2:3]
	v_pk_mul_f32 v[4:5], v[4:5], v[184:185] op_sel_hi:[1,0]
	v_exp_f32_e32 v14, v14
	v_exp_f32_e32 v15, v15
	v_pk_fma_f32 v[12:13], v[12:13], v[186:187], v[186:187] op_sel_hi:[1,0,0]
	v_rcp_f32_e32 v22, v22
	v_rcp_f32_e32 v23, v23
	v_pk_mul_f32 v[16:17], v[16:17], v[20:21]
	v_pk_mul_f32 v[6:7], v[6:7], v[184:185] op_sel_hi:[1,0]
	v_exp_f32_e32 v4, v4
	v_exp_f32_e32 v5, v5
	v_pk_fma_f32 v[14:15], v[14:15], v[186:187], v[186:187] op_sel_hi:[1,0,0]
	v_rcp_f32_e32 v12, v12
	v_rcp_f32_e32 v13, v13
	v_pk_mul_f32 v[18:19], v[18:19], v[22:23]
	v_exp_f32_e32 v6, v6
	v_exp_f32_e32 v7, v7
	v_pk_fma_f32 v[4:5], v[4:5], v[186:187], v[186:187] op_sel_hi:[1,0,0]
	v_rcp_f32_e32 v14, v14
	v_rcp_f32_e32 v15, v15
	v_pk_mul_f32 v[8:9], v[8:9], v[12:13]
	v_mul_u32_u24_e32 v188, s65, v148
	v_mov_b32_e32 v189, 0
	v_cvt_pk_bf16_f32 v28, v24, v25
	v_cvt_pk_bf16_f32 v29, v26, v27
	v_cvt_pk_bf16_f32 v30, v16, v17
	v_cvt_pk_bf16_f32 v31, v18, v19
	v_add_u32_e32 v188, v188, v192
	v_lshl_add_u64 v[188:189], v[188:189], 0, s[8:9]
	s_nop 0
	global_store_dwordx4 v[188:189], v[28:31], off
	v_pk_fma_f32 v[6:7], v[6:7], v[186:187], v[186:187] op_sel_hi:[1,0,0]
	v_rcp_f32_e32 v4, v4
	v_rcp_f32_e32 v5, v5
	v_pk_mul_f32 v[10:11], v[10:11], v[14:15]
	v_rcp_f32_e32 v6, v6
	v_rcp_f32_e32 v7, v7
	v_pk_mul_f32 v[0:1], v[0:1], v[4:5]
	v_pk_mul_f32 v[2:3], v[2:3], v[6:7]
	v_mul_u32_u24_e32 v190, s65, v146
	v_mov_b32_e32 v191, 0
	v_cvt_pk_bf16_f32 v12, v8, v9
	v_cvt_pk_bf16_f32 v13, v10, v11
	v_cvt_pk_bf16_f32 v14, v0, v1
	v_cvt_pk_bf16_f32 v15, v2, v3
	v_add_u32_e32 v190, v190, v192
	v_lshl_add_u64 v[190:191], v[190:191], 0, s[8:9]
	s_nop 0
	global_store_dwordx4 v[190:191], v[12:15], off
	s_andn2_b64 vcc, exec, s[42:43]
	s_mov_b64 s[20:21], -1
	s_cbranch_vccnz .LBB0_64
	s_andn2_b64 vcc, exec, s[6:7]
	s_cbranch_vccnz .LBB0_63
	s_branch .LBB0_63
